# V tile DMA of the next step issued at the very top of the step, K pieces behind the first MFMA
# speedup vs baseline: 1.0123x; 1.0038x over previous
; #define SBAR() __builtin_amdgcn_sched_barrier(0)
; #define KDMA(k0, b) do { const char* g_ = (const char*)(Kh + (long)(k0) * DM); char* l_ = K_lds + (b) * 16384 + wu * 1024; \
;     DMA16(g_ + koff[0], l_); DMA16(g_ + koff[1], l_ + 8192); } while (0)
; #define VDMA(k0, b) do { const char* g_ = (const char*)(Vh + (long)(k0) * DM); char* l_ = V_lds + (b) * 32768 + wu * 1024; \
;     DMA16(g_ + voff[0], l_); DMA16(g_ + voff[1], l_ + 8192); DMA16(g_ + voff[0] + 256, l_ + 16384); DMA16(g_ + voff[1] + 256, l_ + 16384 + 8192); } while (0)
; #define VRD(D0, X) do { X##0 = tr_read<v_rd_off(D0, 0, 0)>(vb); X##1 = tr_read<v_rd_off(D0, 0, 1)>(vb); X##2 = tr_read<v_rd_off(D0, 1, 0)>(vb); X##3 = tr_read<v_rd_off(D0, 1, 1)>(vb); \
;     X##4 = tr_read<v_rd_off(D0, 2, 0)>(vb); X##5 = tr_read<v_rd_off(D0, 2, 1)>(vb); X##6 = tr_read<v_rd_off(D0, 3, 0)>(vb); X##7 = tr_read<v_rd_off(D0, 3, 1)>(vb); } while (0)
; template <int PROBE, int MODE>
; DI void dattn_body(const u16* __restrict__ Qb, const u16* __restrict__ Kh, const u16* __restrict__ Vh, u16* __restrict__ Ob, const u16* __restrict__ O1, float lam, const float* __restrict__ subg, int seq, int q0, float kmax2, char* lds) {
;     ...
;   for (int j = 0; j < NT; ++j) {
;     const bool more = j + 1 < NT;
;     if (!(PROBE & 1)) {
;       if (j + 2 < NT) KDMA((j + 2) * KVBLK, j & 1);
;       if (more) VDMA((j + 1) * KVBLK, (j + 1) & 1);
;     }
;     bf16x8 kf[8];
;     if (more) { const char* Ks_ = K_lds + ((j + 1) & 1) * 16384;
; #pragma unroll
;       for (int d0 = 0; d0 < 8; ++d0) kf[d0] = *reinterpret_cast<const bf16x8*>(Ks_ + KSWZ(32 * kh + r32, (d0 * 16 + hi * 8) * 2)); }
;     const bf16x8 pb0 = *(const bf16x8*)(pr + (j & 1) * 16384), pb1 = *(const bf16x8*)(pr + (j & 1) * 16384 + 16);
;     const int vb = vb0 + (j & 1) * 32768;
;     s16x4 va0, va1, va2, va3, va4, va5, va6, va7, vc0, vc1, vc2, vc3, vc4, vc5, vc6, vc7;
;     VRD(0, va);
;     if (more) { asm volatile("s_waitcnt lgkmcnt(10)" ::: "memory"); SBAR();
.Lfast0:
	s_sub_i32 s72, s18, 64
	s_lshl_b32 s48, s72, 12
	s_add_u32 s48, s16, s48
	s_addc_u32 s49, s17, 0
	s_and_b32 s100, s54, 0x8000
	s_add_i32 s100, s85, s100
	s_mov_b32 m0, s100
	s_add_u32 s74, s48, 0x100
	s_addc_u32 s75, s49, 0
	global_load_lds_dwordx4 v176, s[48:49]
	s_add_i32 m0, s100, 0x2000
	s_nop 0
	global_load_lds_dwordx4 v156, s[48:49]
	s_add_i32 m0, s100, 0x4000
	s_cmp_gt_i32 s72, s87
	s_cselect_b32 s72, s21, s20
	v_sub_f32_e32 v160, s72, v158
	s_and_b32 s101, s25, 0x4000
	s_addk_i32 s25, 0x4000
	s_and_b32 s19, s25, 0x4000
	s_and_b32 s48, s55, 1
	v_lshl_add_u32 v71, s48, 14, v210
	s_bfe_u32 s72, s85, 0x1000a
	s_lshl_b32 s72, s72, 13
	s_lshl_b32 s48, s48, 15
	s_sub_i32 s49, s48, s72
	s_add_i32 s48, s48, s72
	v_add_u32_e32 v216, s48, v212
	v_add_u32_e32 v233, s49, v212
	v_add_u32_e32 v68, s19, v213
	v_add_u32_e32 v64, v68, v198
	v_add_u32_e32 v69, v68, v199
	ds_read_b64_tr_b16 v[234:235], v216 offset:0
	ds_read_b64_tr_b16 v[236:237], v216 offset:0x800
	ds_read_b128 v[64:67], v64
	ds_read_b128 v[118:121], v69
	global_load_lds_dwordx4 v176, s[74:75]
	s_add_i32 m0, s100, 0x6000
	ds_read_b128 v[162:165], v71
	ds_read_b128 v[166:169], v71 offset:16
	v_add_u32_e32 v69, v68, v200
	v_add_u32_e32 v70, v68, v201
	ds_read_b128 v[122:125], v69
	ds_read_b128 v[126:129], v70
	global_load_lds_dwordx4 v156, s[74:75]
	ds_read_b64_tr_b16 v[238:239], v216 offset:0x1000
	ds_read_b64_tr_b16 v[240:241], v216 offset:0x1800
	v_add_u32_e32 v69, v68, v202
	v_add_u32_e32 v70, v68, v203
	ds_read_b128 v[134:137], v69
	ds_read_b128 v[138:141], v70
	v_add_u32_e32 v142, v68, v204
	v_add_u32_e32 v146, v68, v205
	s_waitcnt lgkmcnt(10)
	v_mfma_f32_32x32x16_bf16 v[0:15], v[114:117], v[234:237], v[0:15]
	s_add_i32 s48, s55, 2
	s_cmp_ge_u32 s48, s11
	s_cbranch_scc1 .Lfast0_k_done
	s_lshl_b32 s48, s18, 12
	s_add_u32 s48, s14, s48
	s_addc_u32 s49, s15, 0
	s_add_i32 s100, s82, s101
	s_mov_b32 m0, s100
	s_nop 0
	global_load_lds_dwordx4 v152, s[48:49]
	s_add_i32 m0, s100, 0x2000
	s_nop 0
	global_load_lds_dwordx4 v154, s[48:49]
; #define SBAR() __builtin_amdgcn_sched_barrier(0)
; #define DMAWAIT() asm volatile("s_waitcnt vmcnt(0)" ::: "memory")
; #define SMX_FIN(pbuf) do { _Pragma("unroll") for (int r = 0; r < 16; ++r) l_reg += S[r]; \
;     PK4S(0, po0); PK4S(8, po1); \
;     *(bf16x8*)(pw + (pbuf) * 16384) = po0; *(bf16x8*)(pw + (pbuf) * 16384 + 16) = po1; } while (0)
; #define VRD(D0, X) do { X##0 = tr_read<v_rd_off(D0, 0, 0)>(vb); X##1 = tr_read<v_rd_off(D0, 0, 1)>(vb); X##2 = tr_read<v_rd_off(D0, 1, 0)>(vb); X##3 = tr_read<v_rd_off(D0, 1, 1)>(vb); \
;     X##4 = tr_read<v_rd_off(D0, 2, 0)>(vb); X##5 = tr_read<v_rd_off(D0, 2, 1)>(vb); X##6 = tr_read<v_rd_off(D0, 3, 0)>(vb); X##7 = tr_read<v_rd_off(D0, 3, 1)>(vb); } while (0)
; #define LWAIT() do { asm volatile("s_waitcnt lgkmcnt(0)" ::: "memory"); SBAR(); } while (0)
; #define VMMP(D0, X) do { if (!(PROBE & 8)) VMM(D0, X); } while (0)
; #define SMXP(c) do { if (!(PROBE & 2)) { if (more) SMX_CH(c); } } while (0)
; template <int PROBE, int MODE>
; DI void dattn_body(const u16* __restrict__ Qb, const u16* __restrict__ Kh, const u16* __restrict__ Vh, u16* __restrict__ Ob, const u16* __restrict__ O1, float lam, const float* __restrict__ subg, int seq, int q0, float kmax2, char* lds) {
;     ...
;     if (more) { asm volatile("s_waitcnt lgkmcnt(10)" ::: "memory"); SBAR();
;       if (!(PROBE & 4)) { S = f32x16{};
; #pragma unroll
;       for (int d0 = 0; d0 < 8; ++d0) S = __builtin_amdgcn_mfma_f32_32x32x16_bf16(kf[d0], qr[d0], S, 0, 0, 0); }
;       SBAR(); }
;     const bf16x8 A0 = kh ? pb0 : po0, A1 = kh ? pb1 : po1, A2 = kh ? po0 : pb0, A3 = kh ? po1 : pb1;
;     SMX_SETUP(j + 1)
;     ...
;     LWAIT(); VRD(1, vc); VMMP(0, va); SMXP(0);
;     LWAIT(); VRD(2, va); VMMP(1, vc); SMXP(1);
;     LWAIT(); VRD(3, vc); VMMP(2, va); SMXP(2);
;     LWAIT(); VMMP(3, vc); SMXP(3);
;     if (!(PROBE & 2)) { if (more) SMX_FIN((j + 1) & 1); }
;     DMAWAIT();
;     __syncthreads();
.Lfast0_k_done:
	ds_read_b64_tr_b16 v[242:243], v233 offset:0x2000
	ds_read_b64_tr_b16 v[244:245], v233 offset:0x2800
	s_waitcnt lgkmcnt(11)
	v_mfma_f32_32x32x16_bf16 v[64:79], v[64:67], v[82:85], 0
	ds_read_b128 v[142:145], v142
	ds_read_b128 v[146:149], v146
	s_waitcnt lgkmcnt(12)
	v_mfma_f32_32x32x16_bf16 v[64:79], v[118:121], v[86:89], v[64:79]
	ds_read_b64_tr_b16 v[246:247], v233 offset:0x3000
	ds_read_b64_tr_b16 v[248:249], v233 offset:0x3800
	s_waitcnt lgkmcnt(11)
	v_mfma_f32_32x32x16_bf16 v[64:79], v[122:125], v[90:93], v[64:79]
	s_waitcnt lgkmcnt(10)
	v_mfma_f32_32x32x16_bf16 v[64:79], v[126:129], v[94:97], v[64:79]
	ds_read_b64_tr_b16 v[126:127], v233 offset:0x3200
	ds_read_b64_tr_b16 v[128:129], v233 offset:0x3a00
	s_waitcnt lgkmcnt(10)
	v_mfma_f32_32x32x16_bf16 v[0:15], v[130:133], v[238:241], v[0:15]
	s_waitcnt lgkmcnt(9)
	v_mfma_f32_32x32x16_bf16 v[64:79], v[134:137], v[98:101], v[64:79]
	ds_read_b64_tr_b16 v[134:135], v233 offset:0x2200
	ds_read_b64_tr_b16 v[136:137], v233 offset:0x2a00
	s_waitcnt lgkmcnt(10)
	v_mfma_f32_32x32x16_bf16 v[64:79], v[138:141], v[102:105], v[64:79]
	ds_read_b64_tr_b16 v[138:139], v216 offset:0x200
	ds_read_b64_tr_b16 v[140:141], v216 offset:0xa00
	s_waitcnt lgkmcnt(10)
	v_mfma_f32_32x32x16_bf16 v[0:15], v[162:165], v[242:245], v[0:15]
	s_waitcnt lgkmcnt(9)
	v_mfma_f32_32x32x16_bf16 v[64:79], v[142:145], v[106:109], v[64:79]
	ds_read_b64_tr_b16 v[142:143], v216 offset:0x1200
	ds_read_b64_tr_b16 v[144:145], v216 offset:0x1a00
	s_waitcnt lgkmcnt(10)
	v_mfma_f32_32x32x16_bf16 v[64:79], v[146:149], v[110:113], v[64:79]
	s_waitcnt lgkmcnt(8)
	v_mfma_f32_32x32x16_bf16 v[0:15], v[166:169], v[246:249], v[0:15]
	s_waitcnt lgkmcnt(2)
	v_mfma_f32_32x32x16_bf16 v[16:31], v[114:117], v[138:141], v[16:31]
	ds_read_b64_tr_b16 v[146:147], v216 offset:0x400
	ds_read_b64_tr_b16 v[148:149], v216 offset:0xc00
	s_nop 7
	s_nop 0
	v_fma_f32 v118, v64, s12, v160
	v_fma_f32 v119, v65, s12, v160
	v_fma_f32 v120, v66, s12, v160
	v_fma_f32 v121, v67, s12, v160
	v_fma_f32 v122, v68, s12, v160
	v_fma_f32 v123, v69, s12, v160
	s_waitcnt lgkmcnt(2)
	v_mfma_f32_32x32x16_bf16 v[16:31], v[130:133], v[142:145], v[16:31]
	ds_read_b64_tr_b16 v[142:143], v216 offset:0x1400
	ds_read_b64_tr_b16 v[144:145], v216 offset:0x1c00
	v_fma_f32 v124, v70, s12, v160
	v_fma_f32 v125, v71, s12, v160
	v_exp_f32_e32 v118, v118
	v_exp_f32_e32 v119, v119
	v_exp_f32_e32 v120, v120
	v_exp_f32_e32 v121, v121
	v_fma_f32 v244, v72, s12, v160
	v_fma_f32 v245, v73, s12, v160
	v_mfma_f32_32x32x16_bf16 v[16:31], v[162:165], v[134:137], v[16:31]
	ds_read_b64_tr_b16 v[138:139], v233 offset:0x2400
	ds_read_b64_tr_b16 v[140:141], v233 offset:0x2c00
	v_exp_f32_e32 v122, v122
	v_exp_f32_e32 v123, v123
	v_add_f32_e32 v209, v118, v209
	v_add_f32_e32 v209, v119, v209
	v_fma_f32 v246, v74, s12, v160
	v_fma_f32 v247, v75, s12, v160
	v_fma_f32 v76, v76, s12, v160
	v_fma_f32 v77, v77, s12, v160
	v_mfma_f32_32x32x16_bf16 v[16:31], v[166:169], v[126:129], v[16:31]
	ds_read_b64_tr_b16 v[64:65], v233 offset:0x3400
	ds_read_b64_tr_b16 v[66:67], v233 offset:0x3c00
	v_exp_f32_e32 v124, v124
	v_exp_f32_e32 v125, v125
	v_add_f32_e32 v209, v120, v209
	v_add_f32_e32 v209, v121, v209
	v_add_f32_e32 v209, v122, v209
	v_add_f32_e32 v209, v123, v209
	v_fma_f32 v78, v78, s12, v160
	v_fma_f32 v79, v79, s12, v160
	s_waitcnt lgkmcnt(6)
	v_mfma_f32_32x32x16_bf16 v[32:47], v[114:117], v[146:149], v[32:47]
	v_exp_f32_e32 v244, v244
	v_exp_f32_e32 v245, v245
	v_add_f32_e32 v209, v124, v209
	v_add_f32_e32 v209, v125, v209
	s_waitcnt lgkmcnt(4)
	v_mfma_f32_32x32x16_bf16 v[32:47], v[130:133], v[142:145], v[32:47]
	ds_read_b64_tr_b16 v[142:143], v216 offset:0x600
	ds_read_b64_tr_b16 v[144:145], v216 offset:0xe00
	ds_read_b64_tr_b16 v[126:127], v216 offset:0x1600
	ds_read_b64_tr_b16 v[128:129], v216 offset:0x1e00
	v_exp_f32_e32 v246, v246
	v_exp_f32_e32 v247, v247
	s_waitcnt lgkmcnt(6)
	v_mfma_f32_32x32x16_bf16 v[32:47], v[162:165], v[138:141], v[32:47]
	ds_read_b64_tr_b16 v[134:135], v233 offset:0x2600
	ds_read_b64_tr_b16 v[136:137], v233 offset:0x2e00
	v_exp_f32_e32 v76, v76
	v_exp_f32_e32 v77, v77
	v_add_f32_e32 v209, v244, v209
	v_add_f32_e32 v209, v245, v209
	s_waitcnt lgkmcnt(6)
	v_mfma_f32_32x32x16_bf16 v[32:47], v[166:169], v[64:67], v[32:47]
	ds_read_b64_tr_b16 v[68:69], v233 offset:0x3600
	ds_read_b64_tr_b16 v[70:71], v233 offset:0x3e00
	v_exp_f32_e32 v78, v78
	v_exp_f32_e32 v79, v79
	v_add_f32_e32 v209, v246, v209
	v_add_f32_e32 v209, v247, v209
	s_waitcnt lgkmcnt(6)
	v_mfma_f32_32x32x16_bf16 v[48:63], v[114:117], v[142:145], v[48:63]
	v_add_u32_e32 v64, s19, v211
	v_add_f32_e32 v209, v76, v209
	v_add_f32_e32 v209, v77, v209
	v_cvt_pk_bf16_f32 v114, v118, v119
	v_cvt_pk_bf16_f32 v115, v120, v121
	v_cvt_pk_bf16_f32 v116, v122, v123
	v_cvt_pk_bf16_f32 v117, v124, v125
	s_waitcnt lgkmcnt(4)
	v_mfma_f32_32x32x16_bf16 v[48:63], v[130:133], v[126:129], v[48:63]
	v_add_f32_e32 v209, v78, v209
	v_add_f32_e32 v209, v79, v209
	v_permlane32_swap_b32_e32 v114, v116
	v_permlane32_swap_b32_e32 v115, v117
	v_cvt_pk_bf16_f32 v130, v244, v245
	v_cvt_pk_bf16_f32 v131, v246, v247
	v_cvt_pk_bf16_f32 v132, v76, v77
	v_cvt_pk_bf16_f32 v133, v78, v79
	ds_write_b128 v64, v[114:117]
	s_waitcnt lgkmcnt(3)
	v_mfma_f32_32x32x16_bf16 v[48:63], v[162:165], v[134:137], v[48:63]
	v_permlane32_swap_b32_e32 v130, v132
	v_permlane32_swap_b32_e32 v131, v133
	ds_write_b128 v64, v[130:133] offset:16
	s_add_i32 s55, s55, 1
	s_add_i32 s18, s18, 64
	s_add_i32 s54, s54, 0x8000
	s_add_i32 s100, s18, -1
	s_cmp_ge_i32 s100, s33
	s_cselect_b32 s100, 1, 0
	s_sub_i32 s101, s18, 64
	s_cmp_le_i32 s101, s35
	s_cselect_b32 s101, 1, 0
	s_and_b32 s100, s100, s101
	s_cmp_eq_u32 s83, s55
	s_waitcnt vmcnt(0) lgkmcnt(0)
	s_barrier
	v_mfma_f32_32x32x16_bf16 v[48:63], v[166:169], v[68:71], v[48:63]
	s_cbranch_scc1 .LBB0_265
	s_cmp_lg_u32 s100, 0
	s_cbranch_scc1 .Lgen0
	s_branch .Lfast0

; #define SBAR() __builtin_amdgcn_sched_barrier(0)
; #define KDMA(k0, b) do { const char* g_ = (const char*)(Kh + (long)(k0) * DM); char* l_ = K_lds + (b) * 16384 + wu * 1024; \
;     DMA16(g_ + koff[0], l_); DMA16(g_ + koff[1], l_ + 8192); } while (0)
; #define VDMA(k0, b) do { const char* g_ = (const char*)(Vh + (long)(k0) * DM); char* l_ = V_lds + (b) * 32768 + wu * 1024; \
;     DMA16(g_ + voff[0], l_); DMA16(g_ + voff[1], l_ + 8192); DMA16(g_ + voff[0] + 256, l_ + 16384); DMA16(g_ + voff[1] + 256, l_ + 16384 + 8192); } while (0)
; #define VRD(D0, X) do { X##0 = tr_read<v_rd_off(D0, 0, 0)>(vb); X##1 = tr_read<v_rd_off(D0, 0, 1)>(vb); X##2 = tr_read<v_rd_off(D0, 1, 0)>(vb); X##3 = tr_read<v_rd_off(D0, 1, 1)>(vb); \
;     X##4 = tr_read<v_rd_off(D0, 2, 0)>(vb); X##5 = tr_read<v_rd_off(D0, 2, 1)>(vb); X##6 = tr_read<v_rd_off(D0, 3, 0)>(vb); X##7 = tr_read<v_rd_off(D0, 3, 1)>(vb); } while (0)
; template <int PROBE, int MODE>
; DI void dattn_body(const u16* __restrict__ Qb, const u16* __restrict__ Kh, const u16* __restrict__ Vh, u16* __restrict__ Ob, const u16* __restrict__ O1, float lam, const float* __restrict__ subg, int seq, int q0, float kmax2, char* lds) {
;     ...
;   for (int j = 0; j < NT; ++j) {
;     const bool more = j + 1 < NT;
;     if (!(PROBE & 1)) {
;       if (j + 2 < NT) KDMA((j + 2) * KVBLK, j & 1);
;       if (more) VDMA((j + 1) * KVBLK, (j + 1) & 1);
;     }
;     bf16x8 kf[8];
;     if (more) { const char* Ks_ = K_lds + ((j + 1) & 1) * 16384;
; #pragma unroll
;       for (int d0 = 0; d0 < 8; ++d0) kf[d0] = *reinterpret_cast<const bf16x8*>(Ks_ + KSWZ(32 * kh + r32, (d0 * 16 + hi * 8) * 2)); }
;     const bf16x8 pb0 = *(const bf16x8*)(pr + (j & 1) * 16384), pb1 = *(const bf16x8*)(pr + (j & 1) * 16384 + 16);
;     const int vb = vb0 + (j & 1) * 32768;
;     s16x4 va0, va1, va2, va3, va4, va5, va6, va7, vc0, vc1, vc2, vc3, vc4, vc5, vc6, vc7;
;     VRD(0, va);
;     if (more) { asm volatile("s_waitcnt lgkmcnt(10)" ::: "memory"); SBAR();
.Lfast1:
	s_sub_i32 s72, s0, 64
	s_lshl_b32 s4, s72, 12
	s_add_u32 s4, s16, s4
	s_addc_u32 s5, s17, 0
	s_and_b32 s100, s25, 0x8000
	s_add_i32 s100, s39, s100
	s_mov_b32 m0, s100
	s_add_u32 s18, s4, 0x100
	s_addc_u32 s19, s5, 0
	global_load_lds_dwordx4 v152, s[4:5]
	s_add_i32 m0, s100, 0x2000
	s_nop 0
	global_load_lds_dwordx4 v156, s[4:5]
	s_add_i32 m0, s100, 0x4000
	s_cmp_gt_i32 s72, s87
	s_cselect_b32 s72, s21, s20
	v_sub_f32_e32 v160, s72, v158
	s_and_b32 s101, s24, 0x4000
	s_addk_i32 s24, 0x4000
	s_and_b32 s1, s24, 0x4000
	s_and_b32 s4, s40, 1
	v_lshl_add_u32 v71, s4, 14, v209
	s_bfe_u32 s72, s39, 0x1000a
	s_lshl_b32 s72, s72, 13
	s_lshl_b32 s4, s4, 15
	s_sub_i32 s5, s4, s72
	s_add_i32 s4, s4, s72
	v_add_u32_e32 v215, s4, v211
	v_add_u32_e32 v233, s5, v211
	v_add_u32_e32 v68, s1, v212
	v_add_u32_e32 v64, v68, v196
	v_add_u32_e32 v69, v68, v198
	ds_read_b64_tr_b16 v[234:235], v215 offset:0
	ds_read_b64_tr_b16 v[236:237], v215 offset:0x800
	ds_read_b128 v[64:67], v64
	ds_read_b128 v[118:121], v69
	global_load_lds_dwordx4 v152, s[18:19]
	s_add_i32 m0, s100, 0x6000
	ds_read_b128 v[162:165], v71
	ds_read_b128 v[166:169], v71 offset:16
	v_add_u32_e32 v69, v68, v199
	v_add_u32_e32 v70, v68, v200
	ds_read_b128 v[122:125], v69
	ds_read_b128 v[126:129], v70
	global_load_lds_dwordx4 v156, s[18:19]
	ds_read_b64_tr_b16 v[238:239], v215 offset:0x1000
	ds_read_b64_tr_b16 v[240:241], v215 offset:0x1800
	v_add_u32_e32 v69, v68, v201
	v_add_u32_e32 v70, v68, v202
	ds_read_b128 v[134:137], v69
	ds_read_b128 v[138:141], v70
	v_add_u32_e32 v142, v68, v203
	v_add_u32_e32 v146, v68, v204
	s_waitcnt lgkmcnt(10)
	v_mfma_f32_32x32x16_bf16 v[0:15], v[114:117], v[234:237], v[0:15]
	s_add_i32 s4, s40, 2
	s_cmp_ge_u32 s4, s11
	s_cbranch_scc1 .Lfast1_k_done
	s_lshl_b32 s4, s0, 12
	s_add_u32 s4, s14, s4
	s_addc_u32 s5, s15, 0
	s_add_u32 s4, s4, 0x100
	s_addc_u32 s5, s5, 0
	s_add_i32 s100, s38, s101
	s_mov_b32 m0, s100
	s_nop 0
	global_load_lds_dwordx4 v176, s[4:5]
	s_add_i32 m0, s100, 0x2000
	s_nop 0
	global_load_lds_dwordx4 v154, s[4:5]
; #define SBAR() __builtin_amdgcn_sched_barrier(0)
; #define DMAWAIT() asm volatile("s_waitcnt vmcnt(0)" ::: "memory")
; #define SMX_FIN(pbuf) do { _Pragma("unroll") for (int r = 0; r < 16; ++r) l_reg += S[r]; \
;     PK4S(0, po0); PK4S(8, po1); \
;     *(bf16x8*)(pw + (pbuf) * 16384) = po0; *(bf16x8*)(pw + (pbuf) * 16384 + 16) = po1; } while (0)
; #define VRD(D0, X) do { X##0 = tr_read<v_rd_off(D0, 0, 0)>(vb); X##1 = tr_read<v_rd_off(D0, 0, 1)>(vb); X##2 = tr_read<v_rd_off(D0, 1, 0)>(vb); X##3 = tr_read<v_rd_off(D0, 1, 1)>(vb); \
;     X##4 = tr_read<v_rd_off(D0, 2, 0)>(vb); X##5 = tr_read<v_rd_off(D0, 2, 1)>(vb); X##6 = tr_read<v_rd_off(D0, 3, 0)>(vb); X##7 = tr_read<v_rd_off(D0, 3, 1)>(vb); } while (0)
; #define LWAIT() do { asm volatile("s_waitcnt lgkmcnt(0)" ::: "memory"); SBAR(); } while (0)
; #define VMMP(D0, X) do { if (!(PROBE & 8)) VMM(D0, X); } while (0)
; #define SMXP(c) do { if (!(PROBE & 2)) { if (more) SMX_CH(c); } } while (0)
; template <int PROBE, int MODE>
; DI void dattn_body(const u16* __restrict__ Qb, const u16* __restrict__ Kh, const u16* __restrict__ Vh, u16* __restrict__ Ob, const u16* __restrict__ O1, float lam, const float* __restrict__ subg, int seq, int q0, float kmax2, char* lds) {
;     ...
;     if (more) { asm volatile("s_waitcnt lgkmcnt(10)" ::: "memory"); SBAR();
;       if (!(PROBE & 4)) { S = f32x16{};
; #pragma unroll
;       for (int d0 = 0; d0 < 8; ++d0) S = __builtin_amdgcn_mfma_f32_32x32x16_bf16(kf[d0], qr[d0], S, 0, 0, 0); }
;       SBAR(); }
;     const bf16x8 A0 = kh ? pb0 : po0, A1 = kh ? pb1 : po1, A2 = kh ? po0 : pb0, A3 = kh ? po1 : pb1;
;     SMX_SETUP(j + 1)
;     ...
;     LWAIT(); VRD(1, vc); VMMP(0, va); SMXP(0);
;     LWAIT(); VRD(2, va); VMMP(1, vc); SMXP(1);
;     LWAIT(); VRD(3, vc); VMMP(2, va); SMXP(2);
;     LWAIT(); VMMP(3, vc); SMXP(3);
;     if (!(PROBE & 2)) { if (more) SMX_FIN((j + 1) & 1); }
;     DMAWAIT();
;     __syncthreads();
.Lfast1_k_done:
	ds_read_b64_tr_b16 v[242:243], v233 offset:0x2000
	ds_read_b64_tr_b16 v[244:245], v233 offset:0x2800
	s_waitcnt lgkmcnt(11)
	v_mfma_f32_32x32x16_bf16 v[64:79], v[64:67], v[82:85], 0
	ds_read_b128 v[142:145], v142
	ds_read_b128 v[146:149], v146
	s_waitcnt lgkmcnt(12)
	v_mfma_f32_32x32x16_bf16 v[64:79], v[118:121], v[86:89], v[64:79]
	ds_read_b64_tr_b16 v[246:247], v233 offset:0x3000
	ds_read_b64_tr_b16 v[248:249], v233 offset:0x3800
	s_waitcnt lgkmcnt(11)
	v_mfma_f32_32x32x16_bf16 v[64:79], v[122:125], v[90:93], v[64:79]
	s_waitcnt lgkmcnt(10)
	v_mfma_f32_32x32x16_bf16 v[64:79], v[126:129], v[94:97], v[64:79]
	ds_read_b64_tr_b16 v[126:127], v233 offset:0x3200
	ds_read_b64_tr_b16 v[128:129], v233 offset:0x3a00
	s_waitcnt lgkmcnt(10)
	v_mfma_f32_32x32x16_bf16 v[0:15], v[130:133], v[238:241], v[0:15]
	s_waitcnt lgkmcnt(9)
	v_mfma_f32_32x32x16_bf16 v[64:79], v[134:137], v[98:101], v[64:79]
	ds_read_b64_tr_b16 v[134:135], v233 offset:0x2200
	ds_read_b64_tr_b16 v[136:137], v233 offset:0x2a00
	s_waitcnt lgkmcnt(10)
	v_mfma_f32_32x32x16_bf16 v[64:79], v[138:141], v[102:105], v[64:79]
	ds_read_b64_tr_b16 v[138:139], v215 offset:0x200
	ds_read_b64_tr_b16 v[140:141], v215 offset:0xa00
	s_waitcnt lgkmcnt(10)
	v_mfma_f32_32x32x16_bf16 v[0:15], v[162:165], v[242:245], v[0:15]
	s_waitcnt lgkmcnt(9)
	v_mfma_f32_32x32x16_bf16 v[64:79], v[142:145], v[106:109], v[64:79]
	ds_read_b64_tr_b16 v[142:143], v215 offset:0x1200
	ds_read_b64_tr_b16 v[144:145], v215 offset:0x1a00
	s_waitcnt lgkmcnt(10)
	v_mfma_f32_32x32x16_bf16 v[64:79], v[146:149], v[110:113], v[64:79]
	s_waitcnt lgkmcnt(8)
	v_mfma_f32_32x32x16_bf16 v[0:15], v[166:169], v[246:249], v[0:15]
	s_waitcnt lgkmcnt(2)
	v_mfma_f32_32x32x16_bf16 v[16:31], v[114:117], v[138:141], v[16:31]
	ds_read_b64_tr_b16 v[146:147], v215 offset:0x400
	ds_read_b64_tr_b16 v[148:149], v215 offset:0xc00
	s_nop 7
	s_nop 0
	v_fma_f32 v118, v64, s12, v160
	v_fma_f32 v119, v65, s12, v160
	v_fma_f32 v120, v66, s12, v160
	v_fma_f32 v121, v67, s12, v160
	v_fma_f32 v122, v68, s12, v160
	v_fma_f32 v123, v69, s12, v160
	s_waitcnt lgkmcnt(2)
	v_mfma_f32_32x32x16_bf16 v[16:31], v[130:133], v[142:145], v[16:31]
	ds_read_b64_tr_b16 v[142:143], v215 offset:0x1400
	ds_read_b64_tr_b16 v[144:145], v215 offset:0x1c00
	v_fma_f32 v124, v70, s12, v160
	v_fma_f32 v125, v71, s12, v160
	v_exp_f32_e32 v118, v118
	v_exp_f32_e32 v119, v119
	v_exp_f32_e32 v120, v120
	v_exp_f32_e32 v121, v121
	v_fma_f32 v244, v72, s12, v160
	v_fma_f32 v245, v73, s12, v160
	v_mfma_f32_32x32x16_bf16 v[16:31], v[162:165], v[134:137], v[16:31]
	ds_read_b64_tr_b16 v[138:139], v233 offset:0x2400
	ds_read_b64_tr_b16 v[140:141], v233 offset:0x2c00
	v_exp_f32_e32 v122, v122
	v_exp_f32_e32 v123, v123
	v_add_f32_e32 v208, v118, v208
	v_add_f32_e32 v208, v119, v208
	v_fma_f32 v246, v74, s12, v160
	v_fma_f32 v247, v75, s12, v160
	v_fma_f32 v76, v76, s12, v160
	v_fma_f32 v77, v77, s12, v160
	v_mfma_f32_32x32x16_bf16 v[16:31], v[166:169], v[126:129], v[16:31]
	ds_read_b64_tr_b16 v[64:65], v233 offset:0x3400
	ds_read_b64_tr_b16 v[66:67], v233 offset:0x3c00
	v_exp_f32_e32 v124, v124
	v_exp_f32_e32 v125, v125
	v_add_f32_e32 v208, v120, v208
	v_add_f32_e32 v208, v121, v208
	v_add_f32_e32 v208, v122, v208
	v_add_f32_e32 v208, v123, v208
	v_fma_f32 v78, v78, s12, v160
	v_fma_f32 v79, v79, s12, v160
	s_waitcnt lgkmcnt(6)
	v_mfma_f32_32x32x16_bf16 v[32:47], v[114:117], v[146:149], v[32:47]
	v_exp_f32_e32 v244, v244
	v_exp_f32_e32 v245, v245
	v_add_f32_e32 v208, v124, v208
	v_add_f32_e32 v208, v125, v208
	s_waitcnt lgkmcnt(4)
	v_mfma_f32_32x32x16_bf16 v[32:47], v[130:133], v[142:145], v[32:47]
	ds_read_b64_tr_b16 v[142:143], v215 offset:0x600
	ds_read_b64_tr_b16 v[144:145], v215 offset:0xe00
	ds_read_b64_tr_b16 v[126:127], v215 offset:0x1600
	ds_read_b64_tr_b16 v[128:129], v215 offset:0x1e00
	v_exp_f32_e32 v246, v246
	v_exp_f32_e32 v247, v247
	s_waitcnt lgkmcnt(6)
	v_mfma_f32_32x32x16_bf16 v[32:47], v[162:165], v[138:141], v[32:47]
	ds_read_b64_tr_b16 v[134:135], v233 offset:0x2600
	ds_read_b64_tr_b16 v[136:137], v233 offset:0x2e00
	v_exp_f32_e32 v76, v76
	v_exp_f32_e32 v77, v77
	v_add_f32_e32 v208, v244, v208
	v_add_f32_e32 v208, v245, v208
	s_waitcnt lgkmcnt(6)
	v_mfma_f32_32x32x16_bf16 v[32:47], v[166:169], v[64:67], v[32:47]
	ds_read_b64_tr_b16 v[68:69], v233 offset:0x3600
	ds_read_b64_tr_b16 v[70:71], v233 offset:0x3e00
	v_exp_f32_e32 v78, v78
	v_exp_f32_e32 v79, v79
	v_add_f32_e32 v208, v246, v208
	v_add_f32_e32 v208, v247, v208
	s_waitcnt lgkmcnt(6)
	v_mfma_f32_32x32x16_bf16 v[48:63], v[114:117], v[142:145], v[48:63]
	v_add_u32_e32 v64, s1, v210
	v_add_f32_e32 v208, v76, v208
	v_add_f32_e32 v208, v77, v208
	v_cvt_pk_bf16_f32 v114, v118, v119
	v_cvt_pk_bf16_f32 v115, v120, v121
	v_cvt_pk_bf16_f32 v116, v122, v123
	v_cvt_pk_bf16_f32 v117, v124, v125
	s_waitcnt lgkmcnt(4)
	v_mfma_f32_32x32x16_bf16 v[48:63], v[130:133], v[126:129], v[48:63]
	v_add_f32_e32 v208, v78, v208
	v_add_f32_e32 v208, v79, v208
	v_permlane32_swap_b32_e32 v114, v116
	v_permlane32_swap_b32_e32 v115, v117
	v_cvt_pk_bf16_f32 v130, v244, v245
	v_cvt_pk_bf16_f32 v131, v246, v247
	v_cvt_pk_bf16_f32 v132, v76, v77
	v_cvt_pk_bf16_f32 v133, v78, v79
	ds_write_b128 v64, v[114:117]
	s_waitcnt lgkmcnt(3)
	v_mfma_f32_32x32x16_bf16 v[48:63], v[162:165], v[134:137], v[48:63]
	v_permlane32_swap_b32_e32 v130, v132
	v_permlane32_swap_b32_e32 v131, v133
	ds_write_b128 v64, v[130:133] offset:16
	s_add_i32 s40, s40, 1
	s_add_i32 s0, s0, 64
	s_add_i32 s25, s25, 0x8000
	s_add_i32 s100, s0, -1
	s_cmp_ge_i32 s100, s33
	s_cselect_b32 s100, 1, 0
	s_sub_i32 s101, s0, 64
	s_cmp_le_i32 s101, s35
	s_cselect_b32 s101, 1, 0
	s_and_b32 s100, s100, s101
	s_cmp_eq_u32 s83, s40
	s_waitcnt vmcnt(0) lgkmcnt(0)
	s_barrier
	v_mfma_f32_32x32x16_bf16 v[48:63], v[166:169], v[68:71], v[48:63]
	s_cbranch_scc1 .LBB0_303
	s_cmp_lg_u32 s100, 0
	s_cbranch_scc1 .Lgen1
	s_branch .Lfast1
